# row phases (pre-mixer / post-mixer / post-mlp residual+norm+modulate): hand-written loops, all loads of a row issued together, DPP+readlane wave sums
# speedup vs baseline: 1.0302x; 1.0199x over previous
; DI f32x4 bf4_to_f4(u32x2 w) { return (f32x4){__uint_as_float(w.x << 16), __uint_as_float(w.x & 0xffff0000u), __uint_as_float(w.y << 16), __uint_as_float(w.y & 0xffff0000u)}; }
; DI void row_phase(const PZ& p, int layer, int mode, int wave, int lane) {
;     const int gw = blockIdx.x * 8 + wave, NGW = gridDim.x * 8;
;     const bool from_in = (layer == 0);
;     const float* xl_src = from_in ? p.in(0) : p.out();
;     const float* xc_src = from_in ? p.in(2) : (const float*)(p.ws() + WS_XC);
;     float* xc_dst = (float*)(p.ws() + WS_XC);
;     const float* MOD = (const float*)(p.ws() + WS_MOD);
;     const float* modl = MOD + (size_t)layer * 33 * 6144;
;     const float* gpm = p.in(7) + layer * 1024;
;     const float* gpl = p.in(9) + layer * 1024;
;     const int hl = mode == 2 ? layer + 1 : layer;
;     const bool do_h = hl < 4;
;     const float* gpre = (mode == 1 ? p.in(8) : p.in(6)) + (do_h ? hl : 0) * 1024;
;     const float* modh = MOD + (size_t)(do_h ? hl : 0) * 33 * 6144;
;     const int shift_i = mode == 1 ? 3 : 0, scale_i = mode == 1 ? 4 : 1;
;     bf16_t* HAo = (bf16_t*)(p.ws() + ((hl == 2 && mode != 1) ? WS_BIG : WS_HA));
;     const bf16_t* Y = (const bf16_t*)(p.ws() + WS_Y);
;     const bf16_t* F = (const bf16_t*)(p.ws() + WS_HA);
;     for (int m = gw; m < MTOK; m += NGW) {
;         const int b = m / TT, t = m - b * TT; const bool isc = t < NCTX; const int mr = isc ? 32 : b;
;         if (isc && layer == 3 && mode != 0) continue;
;         const size_t xoff = isc ? (size_t)(b * NCTX + t) * 1024 : (size_t)(b * NLAT + t - NCTX) * 1024;
;         const float* xs = (isc ? xc_src : xl_src) + xoff;
;         float* xd = (isc ? xc_dst : p.out()) + xoff;
;         f32x4 xv[4];
; #pragma unroll
;         for (int j = 0; j < 4; ++j) xv[j] = __builtin_nontemporal_load((const f32x4*)xs + lane + 64 * j);
;         if (mode != 0) {
;             f32x4 yv[4]; float ss = 0.f;
; #pragma unroll
;             for (int j = 0; j < 4; ++j) { yv[j] = bf4_to_f4(__builtin_nontemporal_load((const u32x2*)(Y + (size_t)m * 1024) + lane + 64 * j)); ss += yv[j].x * yv[j].x + yv[j].y * yv[j].y + yv[j].z * yv[j].z + yv[j].w * yv[j].w; }
.LBB0_1582:
	v_readlane_b32 s2, v252, 6
	v_readlane_b32 s3, v255, 30
	s_add_i32 s20, s3, s2
	s_cmp_gt_i32 s20, 0x11fff
	s_mov_b32 s73, s22
	s_cbranch_scc1 .LBB0_1592
	s_load_dwordx2 s[38:39], s[90:91], 0x0
	s_load_dwordx2 s[40:41], s[90:91], 0x10
	s_load_dwordx2 s[42:43], s[90:91], 0x150
	s_load_dwordx2 s[44:45], s[90:91], 0x158
	s_load_dwordx4 s[48:51], s[90:91], 0x30
	s_load_dwordx4 s[52:55], s[90:91], 0x40
	v_readlane_b32 s12, v255, 33
	v_lshlrev_b32_e32 v0, 4, v166
	v_lshlrev_b32_e32 v1, 3, v166
	v_mov_b32_e32 v194, 0x3a800000
	s_waitcnt lgkmcnt(0)
	s_add_i32 s9, s12, 1
	s_cmp_lt_u32 s9, 4
	s_cselect_b32 s30, 1, 0
	s_cselect_b32 s9, s9, 0
	s_lshl_b32 s2, s12, 12
	s_lshl_b32 s3, s9, 12
	s_add_u32 s4, s50, s2
	s_addc_u32 s5, s51, 0
	global_load_dwordx4 v[4:7], v0, s[4:5] offset:0
	global_load_dwordx4 v[8:11], v0, s[4:5] offset:1024
	global_load_dwordx4 v[12:15], v0, s[4:5] offset:2048
	global_load_dwordx4 v[16:19], v0, s[4:5] offset:3072
	s_add_u32 s6, s54, s2
	s_addc_u32 s7, s55, 0
	global_load_dwordx4 v[20:23], v0, s[6:7] offset:0
	global_load_dwordx4 v[24:27], v0, s[6:7] offset:1024
	global_load_dwordx4 v[28:31], v0, s[6:7] offset:2048
	global_load_dwordx4 v[32:35], v0, s[6:7] offset:3072
	s_add_u32 s34, s48, s3
	s_addc_u32 s35, s49, 0
	global_load_dwordx4 v[36:39], v0, s[34:35] offset:0
	global_load_dwordx4 v[40:43], v0, s[34:35] offset:1024
	global_load_dwordx4 v[44:47], v0, s[34:35] offset:2048
	global_load_dwordx4 v[48:51], v0, s[34:35] offset:3072
	s_add_u32 s46, s44, 0x7100000
	s_addc_u32 s47, s45, 0
	s_cmp_eq_u32 s12, 0
	s_cselect_b32 s38, s38, s42
	s_cselect_b32 s39, s39, s43
	s_cselect_b32 s40, s40, s46
	s_cselect_b32 s41, s41, s47
	s_add_u32 s2, s44, 0x6c00000
	s_addc_u32 s3, s45, 0
	s_mul_i32 s4, s12, 0xc6000
	s_mul_i32 s5, s9, 0xc6000
	s_add_u32 s48, s2, s4
	s_addc_u32 s49, s3, 0
	s_add_u32 s50, s2, s5
	s_addc_u32 s51, s3, 0
	s_add_u32 s52, s44, 0x12100000
	s_addc_u32 s53, s45, 0
	s_add_u32 s54, s44, 0x9100000
	s_addc_u32 s55, s45, 0
	s_mov_b32 s3, 0x1b100000
	s_mov_b32 s2, 0x9100000
	s_cmp_eq_u32 s9, 2
	s_cselect_b32 s2, s3, s2
	s_add_u32 s98, s44, s2
	s_addc_u32 s99, s45, 0
	s_branch .Lr2_row
.Lr2_next:
	s_add_i32 s20, s20, s92
	s_cmp_gt_i32 s20, 0x11fff
	s_cbranch_scc1 .LBB0_1592
.Lr2_row:
	s_mul_hi_i32 s21, s20, 0x38e38e39
	s_lshr_b32 s23, s21, 31
	s_ashr_i32 s21, s21, 9
	s_add_i32 s21, s21, s23
	s_mul_i32 s23, s21, 0xfffff700
	s_add_i32 s23, s23, s20
	s_cmpk_lt_i32 s23, 0x100
	s_cbranch_scc0 .Lr2_lat
	s_cmp_eq_u32 s12, 3
	s_cbranch_scc1 .Lr2_next
	s_lshl_b32 s25, s21, 8
	s_add_i32 s25, s25, s23
	s_lshl_b32 s25, s25, 12
	s_add_u32 s2, s40, s25
	s_addc_u32 s3, s41, 0
	s_add_u32 s4, s46, s25
	s_addc_u32 s5, s47, 0
	s_mov_b32 s25, 32
	s_branch .Lr2_have
.Lr2_lat:
	s_lshl_b32 s25, s21, 11
	s_add_i32 s25, s25, s23
	s_add_i32 s25, s25, 0xffffff00
	s_lshl_b32 s25, s25, 12
	s_add_u32 s2, s38, s25
	s_addc_u32 s3, s39, 0
	s_add_u32 s4, s42, s25
	s_addc_u32 s5, s43, 0
	s_mov_b32 s25, s21
.Lr2_have:
	s_mul_i32 s25, s25, 0x6000
	s_lshl_b32 s32, s20, 11
	s_add_u32 s6, s52, s32
	s_addc_u32 s7, s53, 0
	global_load_dwordx2 v[70:71], v1, s[6:7] offset:0 nt
	global_load_dwordx2 v[72:73], v1, s[6:7] offset:512 nt
	global_load_dwordx2 v[74:75], v1, s[6:7] offset:1024 nt
	global_load_dwordx2 v[76:77], v1, s[6:7] offset:1536 nt
	s_add_u32 s8, s54, s32
	s_addc_u32 s9, s55, 0
	global_load_dwordx2 v[78:79], v1, s[8:9] offset:0 nt
	global_load_dwordx2 v[80:81], v1, s[8:9] offset:512 nt
	global_load_dwordx2 v[82:83], v1, s[8:9] offset:1024 nt
	global_load_dwordx2 v[84:85], v1, s[8:9] offset:1536 nt
	global_load_dwordx4 v[52:55], v0, s[2:3] offset:0 nt
	global_load_dwordx4 v[56:59], v0, s[2:3] offset:1024 nt
	global_load_dwordx4 v[60:63], v0, s[2:3] offset:2048 nt
	global_load_dwordx4 v[64:67], v0, s[2:3] offset:3072 nt
	s_add_u32 s44, s98, s32
	s_addc_u32 s45, s99, 0
	s_add_u32 s6, s48, s25
	s_addc_u32 s7, s49, 0
	s_add_u32 s6, s6, 0x2000
	s_addc_u32 s7, s7, 0
	global_load_dwordx4 v[86:89], v0, s[6:7] offset:0
	global_load_dwordx4 v[90:93], v0, s[6:7] offset:1024
	global_load_dwordx4 v[94:97], v0, s[6:7] offset:2048
	global_load_dwordx4 v[98:101], v0, s[6:7] offset:3072
	s_add_u32 s8, s48, s25
	s_addc_u32 s9, s49, 0
	s_add_u32 s8, s8, 0x5000
	s_addc_u32 s9, s9, 0
	global_load_dwordx4 v[110:113], v0, s[8:9] offset:0
	global_load_dwordx4 v[114:117], v0, s[8:9] offset:1024
	global_load_dwordx4 v[118:121], v0, s[8:9] offset:2048
	global_load_dwordx4 v[122:125], v0, s[8:9] offset:3072
	s_add_u32 s34, s50, s25
	s_addc_u32 s35, s51, 0
	global_load_dwordx4 v[126:129], v0, s[34:35] offset:0
	global_load_dwordx4 v[130:133], v0, s[34:35] offset:1024
	global_load_dwordx4 v[134:137], v0, s[34:35] offset:2048
	global_load_dwordx4 v[138:141], v0, s[34:35] offset:3072
	s_add_u32 s6, s34, 0x1000
	s_addc_u32 s7, s35, 0
	global_load_dwordx4 v[170:173], v0, s[6:7] offset:0
	global_load_dwordx4 v[174:177], v0, s[6:7] offset:1024
	global_load_dwordx4 v[178:181], v0, s[6:7] offset:2048
	global_load_dwordx4 v[182:185], v0, s[6:7] offset:3072
	s_waitcnt vmcnt(24)
	v_lshlrev_b32_e32 v212, 16, v70
	v_and_b32_e32 v213, 0xffff0000, v70
	v_lshlrev_b32_e32 v214, 16, v71
	v_and_b32_e32 v215, 0xffff0000, v71
	v_lshlrev_b32_e32 v216, 16, v72
	v_and_b32_e32 v217, 0xffff0000, v72
	v_lshlrev_b32_e32 v218, 16, v73
	v_and_b32_e32 v219, 0xffff0000, v73
	v_lshlrev_b32_e32 v220, 16, v74
	v_and_b32_e32 v221, 0xffff0000, v74
	v_lshlrev_b32_e32 v222, 16, v75
	v_and_b32_e32 v223, 0xffff0000, v75
	v_lshlrev_b32_e32 v224, 16, v76
	v_and_b32_e32 v225, 0xffff0000, v76
	v_lshlrev_b32_e32 v226, 16, v77
	v_and_b32_e32 v227, 0xffff0000, v77
	s_waitcnt vmcnt(20)
; DI f32x4 bf4_to_f4(u32x2 w) { return (f32x4){__uint_as_float(w.x << 16), __uint_as_float(w.x & 0xffff0000u), __uint_as_float(w.y << 16), __uint_as_float(w.y & 0xffff0000u)}; }
; DI void row_phase(const PZ& p, int layer, int mode, int wave, int lane) {
;     ...
;             f32x4 yv[4]; float ss = 0.f;
; #pragma unroll
;             for (int j = 0; j < 4; ++j) { yv[j] = bf4_to_f4(__builtin_nontemporal_load((const u32x2*)(Y + (size_t)m * 1024) + lane + 64 * j)); ss += yv[j].x * yv[j].x + yv[j].y * yv[j].y + yv[j].z * yv[j].z + yv[j].w * yv[j].w; }
;             const float rstd = rsqrtf(wave_sum(ss) * (1.f / 1024.f) + 1e-6f);
; #pragma unroll
;             for (int j = 0; j < 4; ++j) {
;                 const f32x4 gate = *((const f32x4*)(modl + (size_t)mr * 6144 + 2 * 1024) + lane + 64 * j);
;                 const f32x4 gp = *((const f32x4*)gpm + lane + 64 * j);
;                 xv[j] += gate * (yv[j] * rstd * gp);
;             }
;         }
;         if (mode == 2) {
;             f32x4 yv[4]; float ss = 0.f;
; #pragma unroll
;             for (int j = 0; j < 4; ++j) { yv[j] = bf4_to_f4(__builtin_nontemporal_load((const u32x2*)(F + (size_t)m * 1024) + lane + 64 * j)); ss += yv[j].x * yv[j].x + yv[j].y * yv[j].y + yv[j].z * yv[j].z + yv[j].w * yv[j].w; }
;             const float rstd = rsqrtf(wave_sum(ss) * (1.f / 1024.f) + 1e-6f);
; #pragma unroll
;             for (int j = 0; j < 4; ++j) {
;                 const f32x4 gate = *((const f32x4*)(modl + (size_t)mr * 6144 + 5 * 1024) + lane + 64 * j);
;                 const f32x4 gp = *((const f32x4*)gpl + lane + 64 * j);
;                 xv[j] += gate * (yv[j] * rstd * gp);
;                 *((f32x4*)xd + lane + 64 * j) = xv[j];
;             }
	v_lshlrev_b32_e32 v236, 16, v78
	v_and_b32_e32 v237, 0xffff0000, v78
	v_lshlrev_b32_e32 v238, 16, v79
	v_and_b32_e32 v239, 0xffff0000, v79
	v_lshlrev_b32_e32 v240, 16, v80
	v_and_b32_e32 v241, 0xffff0000, v80
	v_lshlrev_b32_e32 v242, 16, v81
	v_and_b32_e32 v243, 0xffff0000, v81
	v_lshlrev_b32_e32 v244, 16, v82
	v_and_b32_e32 v245, 0xffff0000, v82
	v_lshlrev_b32_e32 v246, 16, v83
	v_and_b32_e32 v247, 0xffff0000, v83
	v_lshlrev_b32_e32 v248, 16, v84
	v_and_b32_e32 v249, 0xffff0000, v84
	v_lshlrev_b32_e32 v250, 16, v85
	v_and_b32_e32 v251, 0xffff0000, v85
	v_mul_f32_e32 v186, v212, v212
	v_mul_f32_e32 v187, v216, v216
	v_mul_f32_e32 v188, v220, v220
	v_mul_f32_e32 v189, v224, v224
	v_fmac_f32_e32 v186, v213, v213
	v_fmac_f32_e32 v187, v217, v217
	v_fmac_f32_e32 v188, v221, v221
	v_fmac_f32_e32 v189, v225, v225
	v_fmac_f32_e32 v186, v214, v214
	v_fmac_f32_e32 v187, v218, v218
	v_fmac_f32_e32 v188, v222, v222
	v_fmac_f32_e32 v189, v226, v226
	v_fmac_f32_e32 v186, v215, v215
	v_fmac_f32_e32 v187, v219, v219
	v_fmac_f32_e32 v188, v223, v223
	v_fmac_f32_e32 v189, v227, v227
	v_add_f32_e32 v186, v186, v187
	v_add_f32_e32 v188, v188, v189
	s_nop 0
	v_add_f32_e32 v186, v186, v188
	v_mul_f32_e32 v190, v236, v236
	v_mul_f32_e32 v191, v240, v240
	v_mul_f32_e32 v192, v244, v244
	v_mul_f32_e32 v193, v248, v248
	v_fmac_f32_e32 v190, v237, v237
	v_fmac_f32_e32 v191, v241, v241
	v_fmac_f32_e32 v192, v245, v245
	v_fmac_f32_e32 v193, v249, v249
	v_fmac_f32_e32 v190, v238, v238
	v_fmac_f32_e32 v191, v242, v242
	v_fmac_f32_e32 v192, v246, v246
	v_fmac_f32_e32 v193, v250, v250
	v_fmac_f32_e32 v190, v239, v239
	v_fmac_f32_e32 v191, v243, v243
	v_fmac_f32_e32 v192, v247, v247
	v_fmac_f32_e32 v193, v251, v251
	v_add_f32_e32 v190, v190, v191
	v_add_f32_e32 v192, v192, v193
	s_nop 0
	v_add_f32_e32 v190, v190, v192
	s_nop 1
	v_add_f32_dpp v186, v186, v186 quad_perm:[1,0,3,2] row_mask:0xf bank_mask:0xf bound_ctrl:1
	v_add_f32_dpp v190, v190, v190 quad_perm:[1,0,3,2] row_mask:0xf bank_mask:0xf bound_ctrl:1
	s_nop 1
	v_add_f32_dpp v186, v186, v186 quad_perm:[2,3,0,1] row_mask:0xf bank_mask:0xf bound_ctrl:1
	v_add_f32_dpp v190, v190, v190 quad_perm:[2,3,0,1] row_mask:0xf bank_mask:0xf bound_ctrl:1
	s_nop 1
	v_add_f32_dpp v186, v186, v186 row_half_mirror row_mask:0xf bank_mask:0xf bound_ctrl:1
	v_add_f32_dpp v190, v190, v190 row_half_mirror row_mask:0xf bank_mask:0xf bound_ctrl:1
	s_nop 1
	v_add_f32_dpp v186, v186, v186 row_mirror row_mask:0xf bank_mask:0xf bound_ctrl:1
	v_add_f32_dpp v190, v190, v190 row_mirror row_mask:0xf bank_mask:0xf bound_ctrl:1
	s_nop 1
	v_readlane_b32 s2, v186, 0
	v_readlane_b32 s3, v186, 16
	v_readlane_b32 s25, v186, 32
	v_readlane_b32 s32, v186, 48
	v_readlane_b32 s93, v190, 0
	v_readlane_b32 s21, v190, 16
	v_readlane_b32 s23, v190, 32
	v_readlane_b32 s34, v190, 48
	s_nop 1
	v_mov_b32_e32 v186, s2
	v_mov_b32_e32 v190, s93
	v_add_f32_e32 v186, s3, v186
	v_add_f32_e32 v190, s21, v190
	v_add_f32_e32 v186, s25, v186
	v_add_f32_e32 v190, s23, v190
	v_add_f32_e32 v186, s32, v186
	v_add_f32_e32 v190, s34, v190
	v_fmaak_f32 v186, v194, v186, 0x358637bd
	v_fmaak_f32 v190, v194, v190, 0x358637bd
	v_rsq_f32_e32 v186, v186
	v_rsq_f32_e32 v190, v190
	s_waitcnt vmcnt(8)
	v_mul_f32_e32 v212, v212, v186
	v_mul_f32_e32 v216, v216, v186
	v_mul_f32_e32 v220, v220, v186
	v_mul_f32_e32 v224, v224, v186
	v_mul_f32_e32 v213, v213, v186
	v_mul_f32_e32 v217, v217, v186
	v_mul_f32_e32 v221, v221, v186
	v_mul_f32_e32 v225, v225, v186
	v_mul_f32_e32 v214, v214, v186
	v_mul_f32_e32 v218, v218, v186
	v_mul_f32_e32 v222, v222, v186
	v_mul_f32_e32 v226, v226, v186
	v_mul_f32_e32 v215, v215, v186
	v_mul_f32_e32 v219, v219, v186
	v_mul_f32_e32 v223, v223, v186
	v_mul_f32_e32 v227, v227, v186
	v_mul_f32_e32 v212, v212, v4
	v_mul_f32_e32 v216, v216, v8
	v_mul_f32_e32 v220, v220, v12
	v_mul_f32_e32 v224, v224, v16
	v_mul_f32_e32 v213, v213, v5
	v_mul_f32_e32 v217, v217, v9
	v_mul_f32_e32 v221, v221, v13
	v_mul_f32_e32 v225, v225, v17
	v_mul_f32_e32 v214, v214, v6
	v_mul_f32_e32 v218, v218, v10
	v_mul_f32_e32 v222, v222, v14
	v_mul_f32_e32 v226, v226, v18
	v_mul_f32_e32 v215, v215, v7
	v_mul_f32_e32 v219, v219, v11
	v_mul_f32_e32 v223, v223, v15
	v_mul_f32_e32 v227, v227, v19
	v_fmac_f32_e32 v52, v86, v212
	v_fmac_f32_e32 v56, v90, v216
	v_fmac_f32_e32 v60, v94, v220
	v_fmac_f32_e32 v64, v98, v224
	v_fmac_f32_e32 v53, v87, v213
	v_fmac_f32_e32 v57, v91, v217
	v_fmac_f32_e32 v61, v95, v221
	v_fmac_f32_e32 v65, v99, v225
	v_fmac_f32_e32 v54, v88, v214
	v_fmac_f32_e32 v58, v92, v218
	v_fmac_f32_e32 v62, v96, v222
	v_fmac_f32_e32 v66, v100, v226
	v_fmac_f32_e32 v55, v89, v215
	v_fmac_f32_e32 v59, v93, v219
	v_fmac_f32_e32 v63, v97, v223
	v_fmac_f32_e32 v67, v101, v227
	v_mul_f32_e32 v236, v236, v190
	v_mul_f32_e32 v240, v240, v190
	v_mul_f32_e32 v244, v244, v190
	v_mul_f32_e32 v248, v248, v190
	v_mul_f32_e32 v237, v237, v190
	v_mul_f32_e32 v241, v241, v190
	v_mul_f32_e32 v245, v245, v190
	v_mul_f32_e32 v249, v249, v190
	v_mul_f32_e32 v238, v238, v190
	v_mul_f32_e32 v242, v242, v190
	v_mul_f32_e32 v246, v246, v190
	v_mul_f32_e32 v250, v250, v190
	v_mul_f32_e32 v239, v239, v190
	v_mul_f32_e32 v243, v243, v190
	v_mul_f32_e32 v247, v247, v190
	v_mul_f32_e32 v251, v251, v190
	v_mul_f32_e32 v236, v236, v20
	v_mul_f32_e32 v240, v240, v24
	v_mul_f32_e32 v244, v244, v28
	v_mul_f32_e32 v248, v248, v32
	v_mul_f32_e32 v237, v237, v21
	v_mul_f32_e32 v241, v241, v25
	v_mul_f32_e32 v245, v245, v29
	v_mul_f32_e32 v249, v249, v33
	v_mul_f32_e32 v238, v238, v22
	v_mul_f32_e32 v242, v242, v26
	v_mul_f32_e32 v246, v246, v30
	v_mul_f32_e32 v250, v250, v34
	v_mul_f32_e32 v239, v239, v23
	v_mul_f32_e32 v243, v243, v27
	v_mul_f32_e32 v247, v247, v31
	v_mul_f32_e32 v251, v251, v35
	v_fmac_f32_e32 v52, v110, v236
	v_fmac_f32_e32 v56, v114, v240
	v_fmac_f32_e32 v60, v118, v244
	v_fmac_f32_e32 v64, v122, v248
	v_fmac_f32_e32 v53, v111, v237
	v_fmac_f32_e32 v57, v115, v241
	v_fmac_f32_e32 v61, v119, v245
	v_fmac_f32_e32 v65, v123, v249
	v_fmac_f32_e32 v54, v112, v238
	v_fmac_f32_e32 v58, v116, v242
	v_fmac_f32_e32 v62, v120, v246
	v_fmac_f32_e32 v66, v124, v250
	v_fmac_f32_e32 v55, v113, v239
	v_fmac_f32_e32 v59, v117, v243
	v_fmac_f32_e32 v63, v121, v247
	v_fmac_f32_e32 v67, v125, v251
	global_store_dwordx4 v0, v[52:55], s[4:5] offset:0
	global_store_dwordx4 v0, v[56:59], s[4:5] offset:1024
	global_store_dwordx4 v0, v[60:63], s[4:5] offset:2048
	global_store_dwordx4 v0, v[64:67], s[4:5] offset:3072
	s_cmp_eq_u32 s30, 0
	s_cbranch_scc1 .Lr2_next
; DI u32x2 f4_to_bf4(f32x4 v) { return (u32x2){pk2(v.x, v.y), pk2(v.z, v.w)}; }
; DI void row_phase(const PZ& p, int layer, int mode, int wave, int lane) {
;     ...
;         if (do_h) {
;             float ss = 0.f;
; #pragma unroll
;             for (int j = 0; j < 4; ++j) ss += xv[j].x * xv[j].x + xv[j].y * xv[j].y + xv[j].z * xv[j].z + xv[j].w * xv[j].w;
;             const float rstd = rsqrtf(wave_sum(ss) * (1.f / 1024.f) + 1e-6f);
; #pragma unroll
;             for (int j = 0; j < 4; ++j) {
;                 const f32x4 g = *((const f32x4*)gpre + lane + 64 * j);
;                 const f32x4 sh = *((const f32x4*)(modh + (size_t)mr * 6144 + shift_i * 1024) + lane + 64 * j);
;                 const f32x4 sc = *((const f32x4*)(modh + (size_t)mr * 6144 + scale_i * 1024) + lane + 64 * j);
;                 const f32x4 h = xv[j] * rstd * g * (sc + 1.f) + sh;
;                 *((u32x2*)(HAo + (size_t)m * 1024) + lane + 64 * j) = f4_to_bf4(h);
;             }
	v_mul_f32_e32 v186, v52, v52
	v_mul_f32_e32 v187, v56, v56
	v_mul_f32_e32 v188, v60, v60
	v_mul_f32_e32 v189, v64, v64
	v_fmac_f32_e32 v186, v53, v53
	v_fmac_f32_e32 v187, v57, v57
	v_fmac_f32_e32 v188, v61, v61
	v_fmac_f32_e32 v189, v65, v65
	v_fmac_f32_e32 v186, v54, v54
	v_fmac_f32_e32 v187, v58, v58
	v_fmac_f32_e32 v188, v62, v62
	v_fmac_f32_e32 v189, v66, v66
	v_fmac_f32_e32 v186, v55, v55
	v_fmac_f32_e32 v187, v59, v59
	v_fmac_f32_e32 v188, v63, v63
	v_fmac_f32_e32 v189, v67, v67
	v_add_f32_e32 v186, v186, v187
	v_add_f32_e32 v188, v188, v189
	s_nop 0
	v_add_f32_e32 v186, v186, v188
	s_nop 1
	v_add_f32_dpp v186, v186, v186 quad_perm:[1,0,3,2] row_mask:0xf bank_mask:0xf bound_ctrl:1
	s_nop 1
	v_add_f32_dpp v186, v186, v186 quad_perm:[2,3,0,1] row_mask:0xf bank_mask:0xf bound_ctrl:1
	s_nop 1
	v_add_f32_dpp v186, v186, v186 row_half_mirror row_mask:0xf bank_mask:0xf bound_ctrl:1
	s_nop 1
	v_add_f32_dpp v186, v186, v186 row_mirror row_mask:0xf bank_mask:0xf bound_ctrl:1
	s_nop 1
	v_readlane_b32 s2, v186, 0
	v_readlane_b32 s3, v186, 16
	v_readlane_b32 s25, v186, 32
	v_readlane_b32 s32, v186, 48
	s_nop 1
	v_mov_b32_e32 v186, s2
	v_add_f32_e32 v186, s3, v186
	v_add_f32_e32 v186, s25, v186
	v_add_f32_e32 v186, s32, v186
	v_fmaak_f32 v186, v194, v186, 0x358637bd
	s_nop 0
	v_rsq_f32_e32 v186, v186
	s_waitcnt vmcnt(4)
	v_mul_f32_e32 v52, v52, v186
	v_mul_f32_e32 v56, v56, v186
	v_mul_f32_e32 v60, v60, v186
	v_mul_f32_e32 v64, v64, v186
	v_mul_f32_e32 v53, v53, v186
	v_mul_f32_e32 v57, v57, v186
	v_mul_f32_e32 v61, v61, v186
	v_mul_f32_e32 v65, v65, v186
	v_mul_f32_e32 v54, v54, v186
	v_mul_f32_e32 v58, v58, v186
	v_mul_f32_e32 v62, v62, v186
	v_mul_f32_e32 v66, v66, v186
	v_mul_f32_e32 v55, v55, v186
	v_mul_f32_e32 v59, v59, v186
	v_mul_f32_e32 v63, v63, v186
	v_mul_f32_e32 v67, v67, v186
	v_add_f32_e32 v170, 1.0, v170
	v_add_f32_e32 v174, 1.0, v174
	v_add_f32_e32 v178, 1.0, v178
	v_add_f32_e32 v182, 1.0, v182
	v_add_f32_e32 v171, 1.0, v171
	v_add_f32_e32 v175, 1.0, v175
	v_add_f32_e32 v179, 1.0, v179
	v_add_f32_e32 v183, 1.0, v183
	v_add_f32_e32 v172, 1.0, v172
	v_add_f32_e32 v176, 1.0, v176
	v_add_f32_e32 v180, 1.0, v180
	v_add_f32_e32 v184, 1.0, v184
	v_add_f32_e32 v173, 1.0, v173
	v_add_f32_e32 v177, 1.0, v177
	v_add_f32_e32 v181, 1.0, v181
	v_add_f32_e32 v185, 1.0, v185
	v_mul_f32_e32 v52, v52, v36
	v_mul_f32_e32 v56, v56, v40
	v_mul_f32_e32 v60, v60, v44
	v_mul_f32_e32 v64, v64, v48
	v_mul_f32_e32 v53, v53, v37
	v_mul_f32_e32 v57, v57, v41
	v_mul_f32_e32 v61, v61, v45
	v_mul_f32_e32 v65, v65, v49
	v_mul_f32_e32 v54, v54, v38
	v_mul_f32_e32 v58, v58, v42
	v_mul_f32_e32 v62, v62, v46
	v_mul_f32_e32 v66, v66, v50
	v_mul_f32_e32 v55, v55, v39
	v_mul_f32_e32 v59, v59, v43
	v_mul_f32_e32 v63, v63, v47
	v_mul_f32_e32 v67, v67, v51
	v_fma_f32 v52, v52, v170, v126
	v_fma_f32 v56, v56, v174, v130
	v_fma_f32 v60, v60, v178, v134
	v_fma_f32 v64, v64, v182, v138
	v_fma_f32 v53, v53, v171, v127
	v_fma_f32 v57, v57, v175, v131
	v_fma_f32 v61, v61, v179, v135
	v_fma_f32 v65, v65, v183, v139
	v_fma_f32 v54, v54, v172, v128
	v_fma_f32 v58, v58, v176, v132
	v_fma_f32 v62, v62, v180, v136
	v_fma_f32 v66, v66, v184, v140
	v_fma_f32 v55, v55, v173, v129
	v_fma_f32 v59, v59, v177, v133
	v_fma_f32 v63, v63, v181, v137
	v_fma_f32 v67, v67, v185, v141
	v_cvt_pk_bf16_f32 v186, v52, v53
	v_cvt_pk_bf16_f32 v187, v54, v55
	v_cvt_pk_bf16_f32 v188, v56, v57
	v_cvt_pk_bf16_f32 v189, v58, v59
	v_cvt_pk_bf16_f32 v190, v60, v61
	v_cvt_pk_bf16_f32 v191, v62, v63
	v_cvt_pk_bf16_f32 v192, v64, v65
	v_cvt_pk_bf16_f32 v193, v66, v67
	global_store_dwordx2 v1, v[186:187], s[44:45] offset:0
	global_store_dwordx2 v1, v[188:189], s[44:45] offset:512
	global_store_dwordx2 v1, v[190:191], s[44:45] offset:1024
	global_store_dwordx2 v1, v[192:193], s[44:45] offset:1536
	s_branch .Lr2_next

; DI void row_phase(const PZ& p, int layer, int mode, int wave, int lane) {
;     const int gw = blockIdx.x * 8 + wave, NGW = gridDim.x * 8;
;     const bool from_in = (layer == 0);
;     const float* xl_src = from_in ? p.in(0) : p.out();
;     const float* xc_src = from_in ? p.in(2) : (const float*)(p.ws() + WS_XC);
;     float* xc_dst = (float*)(p.ws() + WS_XC);
;     const float* MOD = (const float*)(p.ws() + WS_MOD);
;     const float* modl = MOD + (size_t)layer * 33 * 6144;
;     const float* gpm = p.in(7) + layer * 1024;
;     const float* gpl = p.in(9) + layer * 1024;
;     const int hl = mode == 2 ? layer + 1 : layer;
;     const bool do_h = hl < 4;
;     const float* gpre = (mode == 1 ? p.in(8) : p.in(6)) + (do_h ? hl : 0) * 1024;
;     const float* modh = MOD + (size_t)(do_h ? hl : 0) * 33 * 6144;
;     const int shift_i = mode == 1 ? 3 : 0, scale_i = mode == 1 ? 4 : 1;
;     bf16_t* HAo = (bf16_t*)(p.ws() + ((hl == 2 && mode != 1) ? WS_BIG : WS_HA));
;     const bf16_t* Y = (const bf16_t*)(p.ws() + WS_Y);
;     const bf16_t* F = (const bf16_t*)(p.ws() + WS_HA);
.LBB0_1600:
	v_readlane_b32 s2, v252, 6
	v_readlane_b32 s3, v255, 30
	s_add_i32 s20, s3, s2
	s_cmp_gt_i32 s20, 0x11fff
	s_mov_b32 s73, s22
	s_cbranch_scc1 .LBB0_1610
	s_load_dwordx2 s[38:39], s[90:91], 0x0
	s_load_dwordx2 s[40:41], s[90:91], 0x10
	s_load_dwordx2 s[42:43], s[90:91], 0x150
	s_load_dwordx2 s[44:45], s[90:91], 0x158
	s_load_dwordx4 s[48:51], s[90:91], 0x30
	s_load_dwordx4 s[52:55], s[90:91], 0x40
	v_readlane_b32 s12, v255, 33
	v_lshlrev_b32_e32 v0, 4, v166
	v_lshlrev_b32_e32 v1, 3, v166
	v_mov_b32_e32 v194, 0x3a800000
	s_waitcnt lgkmcnt(0)
	s_mov_b32 s9, s12
	s_cmp_lt_u32 s9, 4
	s_cselect_b32 s30, 1, 0
	s_cselect_b32 s9, s9, 0
	s_lshl_b32 s2, s12, 12
	s_lshl_b32 s3, s9, 12
	s_add_u32 s4, s50, s2
	s_addc_u32 s5, s51, 0
	global_load_dwordx4 v[4:7], v0, s[4:5] offset:0
	global_load_dwordx4 v[8:11], v0, s[4:5] offset:1024
	global_load_dwordx4 v[12:15], v0, s[4:5] offset:2048
	global_load_dwordx4 v[16:19], v0, s[4:5] offset:3072
	s_add_u32 s34, s52, s3
	s_addc_u32 s35, s53, 0
	global_load_dwordx4 v[36:39], v0, s[34:35] offset:0
	global_load_dwordx4 v[40:43], v0, s[34:35] offset:1024
	global_load_dwordx4 v[44:47], v0, s[34:35] offset:2048
	global_load_dwordx4 v[48:51], v0, s[34:35] offset:3072
	s_add_u32 s46, s44, 0x7100000
	s_addc_u32 s47, s45, 0
	s_cmp_eq_u32 s12, 0
	s_cselect_b32 s38, s38, s42
	s_cselect_b32 s39, s39, s43
	s_cselect_b32 s40, s40, s46
	s_cselect_b32 s41, s41, s47
	s_add_u32 s2, s44, 0x6c00000
	s_addc_u32 s3, s45, 0
	s_mul_i32 s4, s12, 0xc6000
	s_mul_i32 s5, s9, 0xc6000
	s_add_u32 s48, s2, s4
	s_addc_u32 s49, s3, 0
	s_add_u32 s50, s2, s5
	s_addc_u32 s51, s3, 0
	s_add_u32 s52, s44, 0x12100000
	s_addc_u32 s53, s45, 0
	s_add_u32 s54, s44, 0x9100000
	s_addc_u32 s55, s45, 0
	s_mov_b32 s2, 0x9100000
	s_add_u32 s98, s44, s2
	s_addc_u32 s99, s45, 0
	s_branch .Lr1_row

; DI f32x4 bf4_to_f4(u32x2 w) { return (f32x4){__uint_as_float(w.x << 16), __uint_as_float(w.x & 0xffff0000u), __uint_as_float(w.y << 16), __uint_as_float(w.y & 0xffff0000u)}; }
; DI void row_phase(const PZ& p, int layer, int mode, int wave, int lane) {
;     ...
;     for (int m = gw; m < MTOK; m += NGW) {
;         const int b = m / TT, t = m - b * TT; const bool isc = t < NCTX; const int mr = isc ? 32 : b;
;         if (isc && layer == 3 && mode != 0) continue;
;         const size_t xoff = isc ? (size_t)(b * NCTX + t) * 1024 : (size_t)(b * NLAT + t - NCTX) * 1024;
;         const float* xs = (isc ? xc_src : xl_src) + xoff;
;         float* xd = (isc ? xc_dst : p.out()) + xoff;
;         f32x4 xv[4];
; #pragma unroll
;         for (int j = 0; j < 4; ++j) xv[j] = __builtin_nontemporal_load((const f32x4*)xs + lane + 64 * j);
;         if (mode != 0) {
;             f32x4 yv[4]; float ss = 0.f;
; #pragma unroll
;             for (int j = 0; j < 4; ++j) { yv[j] = bf4_to_f4(__builtin_nontemporal_load((const u32x2*)(Y + (size_t)m * 1024) + lane + 64 * j)); ss += yv[j].x * yv[j].x + yv[j].y * yv[j].y + yv[j].z * yv[j].z + yv[j].w * yv[j].w; }
;             const float rstd = rsqrtf(wave_sum(ss) * (1.f / 1024.f) + 1e-6f);
; #pragma unroll
;             for (int j = 0; j < 4; ++j) {
;                 const f32x4 gate = *((const f32x4*)(modl + (size_t)mr * 6144 + 2 * 1024) + lane + 64 * j);
;                 const f32x4 gp = *((const f32x4*)gpm + lane + 64 * j);
;                 xv[j] += gate * (yv[j] * rstd * gp);
;             }
;         }
.Lr1_have:
	s_mul_i32 s25, s25, 0x6000
	s_lshl_b32 s32, s20, 11
	s_add_u32 s6, s52, s32
	s_addc_u32 s7, s53, 0
	global_load_dwordx2 v[70:71], v1, s[6:7] offset:0 nt
	global_load_dwordx2 v[72:73], v1, s[6:7] offset:512 nt
	global_load_dwordx2 v[74:75], v1, s[6:7] offset:1024 nt
	global_load_dwordx2 v[76:77], v1, s[6:7] offset:1536 nt
	global_load_dwordx4 v[52:55], v0, s[2:3] offset:0 nt
	global_load_dwordx4 v[56:59], v0, s[2:3] offset:1024 nt
	global_load_dwordx4 v[60:63], v0, s[2:3] offset:2048 nt
	global_load_dwordx4 v[64:67], v0, s[2:3] offset:3072 nt
	s_add_u32 s44, s98, s32
	s_addc_u32 s45, s99, 0
	s_add_u32 s6, s48, s25
	s_addc_u32 s7, s49, 0
	s_add_u32 s6, s6, 0x2000
	s_addc_u32 s7, s7, 0
	global_load_dwordx4 v[86:89], v0, s[6:7] offset:0
	global_load_dwordx4 v[90:93], v0, s[6:7] offset:1024
	global_load_dwordx4 v[94:97], v0, s[6:7] offset:2048
	global_load_dwordx4 v[98:101], v0, s[6:7] offset:3072
	s_add_u32 s34, s50, s25
	s_addc_u32 s35, s51, 0
	s_add_u32 s34, s34, 0x3000
	s_addc_u32 s35, s35, 0
	global_load_dwordx4 v[126:129], v0, s[34:35] offset:0
	global_load_dwordx4 v[130:133], v0, s[34:35] offset:1024
	global_load_dwordx4 v[134:137], v0, s[34:35] offset:2048
	global_load_dwordx4 v[138:141], v0, s[34:35] offset:3072
	s_add_u32 s6, s34, 0x1000
	s_addc_u32 s7, s35, 0
	global_load_dwordx4 v[170:173], v0, s[6:7] offset:0
	global_load_dwordx4 v[174:177], v0, s[6:7] offset:1024
	global_load_dwordx4 v[178:181], v0, s[6:7] offset:2048
	global_load_dwordx4 v[182:185], v0, s[6:7] offset:3072
	s_waitcnt vmcnt(16)
	v_lshlrev_b32_e32 v212, 16, v70
	v_and_b32_e32 v213, 0xffff0000, v70
	v_lshlrev_b32_e32 v214, 16, v71
	v_and_b32_e32 v215, 0xffff0000, v71
	v_lshlrev_b32_e32 v216, 16, v72
	v_and_b32_e32 v217, 0xffff0000, v72
	v_lshlrev_b32_e32 v218, 16, v73
	v_and_b32_e32 v219, 0xffff0000, v73
	v_lshlrev_b32_e32 v220, 16, v74
	v_and_b32_e32 v221, 0xffff0000, v74
	v_lshlrev_b32_e32 v222, 16, v75
	v_and_b32_e32 v223, 0xffff0000, v75
	v_lshlrev_b32_e32 v224, 16, v76
	v_and_b32_e32 v225, 0xffff0000, v76
	v_lshlrev_b32_e32 v226, 16, v77
	v_and_b32_e32 v227, 0xffff0000, v77
	v_mul_f32_e32 v186, v212, v212
	v_mul_f32_e32 v187, v216, v216
	v_mul_f32_e32 v188, v220, v220
	v_mul_f32_e32 v189, v224, v224
	v_fmac_f32_e32 v186, v213, v213
	v_fmac_f32_e32 v187, v217, v217
	v_fmac_f32_e32 v188, v221, v221
	v_fmac_f32_e32 v189, v225, v225
	v_fmac_f32_e32 v186, v214, v214
	v_fmac_f32_e32 v187, v218, v218
	v_fmac_f32_e32 v188, v222, v222
	v_fmac_f32_e32 v189, v226, v226
	v_fmac_f32_e32 v186, v215, v215
	v_fmac_f32_e32 v187, v219, v219
	v_fmac_f32_e32 v188, v223, v223
	v_fmac_f32_e32 v189, v227, v227
	v_add_f32_e32 v186, v186, v187
	v_add_f32_e32 v188, v188, v189
	s_nop 0
	v_add_f32_e32 v186, v186, v188
	s_nop 1
	v_add_f32_dpp v186, v186, v186 quad_perm:[1,0,3,2] row_mask:0xf bank_mask:0xf bound_ctrl:1
	s_nop 1
	v_add_f32_dpp v186, v186, v186 quad_perm:[2,3,0,1] row_mask:0xf bank_mask:0xf bound_ctrl:1
	s_nop 1
	v_add_f32_dpp v186, v186, v186 row_half_mirror row_mask:0xf bank_mask:0xf bound_ctrl:1
	s_nop 1
	v_add_f32_dpp v186, v186, v186 row_mirror row_mask:0xf bank_mask:0xf bound_ctrl:1
	s_nop 1
	v_readlane_b32 s2, v186, 0
	v_readlane_b32 s3, v186, 16
	v_readlane_b32 s25, v186, 32
	v_readlane_b32 s32, v186, 48
	s_nop 1
	v_mov_b32_e32 v186, s2
	v_add_f32_e32 v186, s3, v186
	v_add_f32_e32 v186, s25, v186
	v_add_f32_e32 v186, s32, v186
	v_fmaak_f32 v186, v194, v186, 0x358637bd
	v_rsq_f32_e32 v186, v186
	s_waitcnt vmcnt(8)
	v_mul_f32_e32 v212, v212, v186
	v_mul_f32_e32 v216, v216, v186
	v_mul_f32_e32 v220, v220, v186
	v_mul_f32_e32 v224, v224, v186
	v_mul_f32_e32 v213, v213, v186
	v_mul_f32_e32 v217, v217, v186
	v_mul_f32_e32 v221, v221, v186
	v_mul_f32_e32 v225, v225, v186
	v_mul_f32_e32 v214, v214, v186
	v_mul_f32_e32 v218, v218, v186
	v_mul_f32_e32 v222, v222, v186
	v_mul_f32_e32 v226, v226, v186
	v_mul_f32_e32 v215, v215, v186
	v_mul_f32_e32 v219, v219, v186
	v_mul_f32_e32 v223, v223, v186
	v_mul_f32_e32 v227, v227, v186
	v_mul_f32_e32 v212, v212, v4
	v_mul_f32_e32 v216, v216, v8
	v_mul_f32_e32 v220, v220, v12
	v_mul_f32_e32 v224, v224, v16
	v_mul_f32_e32 v213, v213, v5
	v_mul_f32_e32 v217, v217, v9
	v_mul_f32_e32 v221, v221, v13
	v_mul_f32_e32 v225, v225, v17
	v_mul_f32_e32 v214, v214, v6
	v_mul_f32_e32 v218, v218, v10
	v_mul_f32_e32 v222, v222, v14
	v_mul_f32_e32 v226, v226, v18
	v_mul_f32_e32 v215, v215, v7
	v_mul_f32_e32 v219, v219, v11
	v_mul_f32_e32 v223, v223, v15
	v_mul_f32_e32 v227, v227, v19
	v_fmac_f32_e32 v52, v86, v212
	v_fmac_f32_e32 v56, v90, v216
	v_fmac_f32_e32 v60, v94, v220
	v_fmac_f32_e32 v64, v98, v224
	v_fmac_f32_e32 v53, v87, v213
	v_fmac_f32_e32 v57, v91, v217
	v_fmac_f32_e32 v61, v95, v221
	v_fmac_f32_e32 v65, v99, v225
	v_fmac_f32_e32 v54, v88, v214
	v_fmac_f32_e32 v58, v92, v218
	v_fmac_f32_e32 v62, v96, v222
	v_fmac_f32_e32 v66, v100, v226
	v_fmac_f32_e32 v55, v89, v215
	v_fmac_f32_e32 v59, v93, v219
	v_fmac_f32_e32 v63, v97, v223
	v_fmac_f32_e32 v67, v101, v227
	s_cmp_eq_u32 s30, 0
	s_cbranch_scc1 .Lr1_next
; DI u32x2 f4_to_bf4(f32x4 v) { return (u32x2){pk2(v.x, v.y), pk2(v.z, v.w)}; }
; DI void row_phase(const PZ& p, int layer, int mode, int wave, int lane) {
;     ...
;         if (do_h) {
;             float ss = 0.f;
; #pragma unroll
;             for (int j = 0; j < 4; ++j) ss += xv[j].x * xv[j].x + xv[j].y * xv[j].y + xv[j].z * xv[j].z + xv[j].w * xv[j].w;
;             const float rstd = rsqrtf(wave_sum(ss) * (1.f / 1024.f) + 1e-6f);
; #pragma unroll
;             for (int j = 0; j < 4; ++j) {
;                 const f32x4 g = *((const f32x4*)gpre + lane + 64 * j);
;                 const f32x4 sh = *((const f32x4*)(modh + (size_t)mr * 6144 + shift_i * 1024) + lane + 64 * j);
;                 const f32x4 sc = *((const f32x4*)(modh + (size_t)mr * 6144 + scale_i * 1024) + lane + 64 * j);
;                 const f32x4 h = xv[j] * rstd * g * (sc + 1.f) + sh;
;                 *((u32x2*)(HAo + (size_t)m * 1024) + lane + 64 * j) = f4_to_bf4(h);
;             }
	v_mul_f32_e32 v186, v52, v52
	v_mul_f32_e32 v187, v56, v56
	v_mul_f32_e32 v188, v60, v60
	v_mul_f32_e32 v189, v64, v64
	v_fmac_f32_e32 v186, v53, v53
	v_fmac_f32_e32 v187, v57, v57
	v_fmac_f32_e32 v188, v61, v61
	v_fmac_f32_e32 v189, v65, v65
	v_fmac_f32_e32 v186, v54, v54
	v_fmac_f32_e32 v187, v58, v58
	v_fmac_f32_e32 v188, v62, v62
	v_fmac_f32_e32 v189, v66, v66
	v_fmac_f32_e32 v186, v55, v55
	v_fmac_f32_e32 v187, v59, v59
	v_fmac_f32_e32 v188, v63, v63
	v_fmac_f32_e32 v189, v67, v67
	v_add_f32_e32 v186, v186, v187
	v_add_f32_e32 v188, v188, v189
	s_nop 0
	v_add_f32_e32 v186, v186, v188
	s_nop 1
	v_add_f32_dpp v186, v186, v186 quad_perm:[1,0,3,2] row_mask:0xf bank_mask:0xf bound_ctrl:1
	s_nop 1
	v_add_f32_dpp v186, v186, v186 quad_perm:[2,3,0,1] row_mask:0xf bank_mask:0xf bound_ctrl:1
	s_nop 1
	v_add_f32_dpp v186, v186, v186 row_half_mirror row_mask:0xf bank_mask:0xf bound_ctrl:1
	s_nop 1
	v_add_f32_dpp v186, v186, v186 row_mirror row_mask:0xf bank_mask:0xf bound_ctrl:1
	s_nop 1
	v_readlane_b32 s2, v186, 0
	v_readlane_b32 s3, v186, 16
	v_readlane_b32 s25, v186, 32
	v_readlane_b32 s32, v186, 48
	s_nop 1
	v_mov_b32_e32 v186, s2
	v_add_f32_e32 v186, s3, v186
	v_add_f32_e32 v186, s25, v186
	v_add_f32_e32 v186, s32, v186
	v_fmaak_f32 v186, v194, v186, 0x358637bd
	s_nop 0
	v_rsq_f32_e32 v186, v186
	s_waitcnt vmcnt(0)
	v_mul_f32_e32 v52, v52, v186
	v_mul_f32_e32 v56, v56, v186
	v_mul_f32_e32 v60, v60, v186
	v_mul_f32_e32 v64, v64, v186
	v_mul_f32_e32 v53, v53, v186
	v_mul_f32_e32 v57, v57, v186
	v_mul_f32_e32 v61, v61, v186
	v_mul_f32_e32 v65, v65, v186
	v_mul_f32_e32 v54, v54, v186
	v_mul_f32_e32 v58, v58, v186
	v_mul_f32_e32 v62, v62, v186
	v_mul_f32_e32 v66, v66, v186
	v_mul_f32_e32 v55, v55, v186
	v_mul_f32_e32 v59, v59, v186
	v_mul_f32_e32 v63, v63, v186
	v_mul_f32_e32 v67, v67, v186
	v_add_f32_e32 v170, 1.0, v170
	v_add_f32_e32 v174, 1.0, v174
	v_add_f32_e32 v178, 1.0, v178
	v_add_f32_e32 v182, 1.0, v182
	v_add_f32_e32 v171, 1.0, v171
	v_add_f32_e32 v175, 1.0, v175
	v_add_f32_e32 v179, 1.0, v179
	v_add_f32_e32 v183, 1.0, v183
	v_add_f32_e32 v172, 1.0, v172
	v_add_f32_e32 v176, 1.0, v176
	v_add_f32_e32 v180, 1.0, v180
	v_add_f32_e32 v184, 1.0, v184
	v_add_f32_e32 v173, 1.0, v173
	v_add_f32_e32 v177, 1.0, v177
	v_add_f32_e32 v181, 1.0, v181
	v_add_f32_e32 v185, 1.0, v185
	v_mul_f32_e32 v52, v52, v36
	v_mul_f32_e32 v56, v56, v40
	v_mul_f32_e32 v60, v60, v44
	v_mul_f32_e32 v64, v64, v48
	v_mul_f32_e32 v53, v53, v37
	v_mul_f32_e32 v57, v57, v41
	v_mul_f32_e32 v61, v61, v45
	v_mul_f32_e32 v65, v65, v49
	v_mul_f32_e32 v54, v54, v38
	v_mul_f32_e32 v58, v58, v42
	v_mul_f32_e32 v62, v62, v46
	v_mul_f32_e32 v66, v66, v50
	v_mul_f32_e32 v55, v55, v39
	v_mul_f32_e32 v59, v59, v43
	v_mul_f32_e32 v63, v63, v47
	v_mul_f32_e32 v67, v67, v51
	v_fma_f32 v52, v52, v170, v126
	v_fma_f32 v56, v56, v174, v130
	v_fma_f32 v60, v60, v178, v134
	v_fma_f32 v64, v64, v182, v138
	v_fma_f32 v53, v53, v171, v127
	v_fma_f32 v57, v57, v175, v131
	v_fma_f32 v61, v61, v179, v135
	v_fma_f32 v65, v65, v183, v139
	v_fma_f32 v54, v54, v172, v128
	v_fma_f32 v58, v58, v176, v132
	v_fma_f32 v62, v62, v180, v136
	v_fma_f32 v66, v66, v184, v140
	v_fma_f32 v55, v55, v173, v129
	v_fma_f32 v59, v59, v177, v133
	v_fma_f32 v63, v63, v181, v137
	v_fma_f32 v67, v67, v185, v141
	v_cvt_pk_bf16_f32 v186, v52, v53
	v_cvt_pk_bf16_f32 v187, v54, v55
	v_cvt_pk_bf16_f32 v188, v56, v57
	v_cvt_pk_bf16_f32 v189, v58, v59
	v_cvt_pk_bf16_f32 v190, v60, v61
	v_cvt_pk_bf16_f32 v191, v62, v63
	v_cvt_pk_bf16_f32 v192, v64, v65
	v_cvt_pk_bf16_f32 v193, v66, v67
	global_store_dwordx2 v1, v[186:187], s[44:45] offset:0
	global_store_dwordx2 v1, v[188:189], s[44:45] offset:512
	global_store_dwordx2 v1, v[190:191], s[44:45] offset:1024
	global_store_dwordx2 v1, v[192:193], s[44:45] offset:1536
	s_branch .Lr1_next

; DI void row_phase(const PZ& p, int layer, int mode, int wave, int lane) {
;     const int gw = blockIdx.x * 8 + wave, NGW = gridDim.x * 8;
;     const bool from_in = (layer == 0);
;     const float* xl_src = from_in ? p.in(0) : p.out();
;     const float* xc_src = from_in ? p.in(2) : (const float*)(p.ws() + WS_XC);
;     float* xc_dst = (float*)(p.ws() + WS_XC);
;     const float* MOD = (const float*)(p.ws() + WS_MOD);
;     const float* modl = MOD + (size_t)layer * 33 * 6144;
;     const float* gpm = p.in(7) + layer * 1024;
;     const float* gpl = p.in(9) + layer * 1024;
;     const int hl = mode == 2 ? layer + 1 : layer;
;     const bool do_h = hl < 4;
;     const float* gpre = (mode == 1 ? p.in(8) : p.in(6)) + (do_h ? hl : 0) * 1024;
;     const float* modh = MOD + (size_t)(do_h ? hl : 0) * 33 * 6144;
;     const int shift_i = mode == 1 ? 3 : 0, scale_i = mode == 1 ? 4 : 1;
;     bf16_t* HAo = (bf16_t*)(p.ws() + ((hl == 2 && mode != 1) ? WS_BIG : WS_HA));
;     const bf16_t* Y = (const bf16_t*)(p.ws() + WS_Y);
;     const bf16_t* F = (const bf16_t*)(p.ws() + WS_HA);
.LBB0_1619:
	v_readlane_b32 s2, v252, 6
	v_readlane_b32 s3, v255, 30
	s_add_i32 s20, s3, s2
	s_cmp_gt_i32 s20, 0x11fff
	s_cbranch_scc1 .LBB0_1628
	s_load_dwordx2 s[38:39], s[90:91], 0x0
	s_load_dwordx2 s[40:41], s[90:91], 0x10
	s_load_dwordx2 s[42:43], s[90:91], 0x150
	s_load_dwordx2 s[44:45], s[90:91], 0x158
	s_load_dwordx4 s[48:51], s[90:91], 0x30
	s_load_dwordx4 s[52:55], s[90:91], 0x40
	v_readlane_b32 s12, v255, 33
	v_lshlrev_b32_e32 v0, 4, v166
	v_lshlrev_b32_e32 v1, 3, v166
	v_mov_b32_e32 v194, 0x3a800000
	s_waitcnt lgkmcnt(0)
	s_mov_b32 s9, s12
	s_cmp_lt_u32 s9, 4
	s_cselect_b32 s30, 1, 0
	s_cselect_b32 s9, s9, 0
	s_lshl_b32 s2, s12, 12
	s_lshl_b32 s3, s9, 12
	s_add_u32 s34, s48, s3
	s_addc_u32 s35, s49, 0
	global_load_dwordx4 v[36:39], v0, s[34:35] offset:0
	global_load_dwordx4 v[40:43], v0, s[34:35] offset:1024
	global_load_dwordx4 v[44:47], v0, s[34:35] offset:2048
	global_load_dwordx4 v[48:51], v0, s[34:35] offset:3072
	s_add_u32 s46, s44, 0x7100000
	s_addc_u32 s47, s45, 0
	s_cmp_eq_u32 s12, 0
	s_cselect_b32 s38, s38, s42
	s_cselect_b32 s39, s39, s43
	s_cselect_b32 s40, s40, s46
	s_cselect_b32 s41, s41, s47
	s_add_u32 s2, s44, 0x6c00000
	s_addc_u32 s3, s45, 0
	s_mul_i32 s4, s12, 0xc6000
	s_mul_i32 s5, s9, 0xc6000
	s_add_u32 s48, s2, s4
	s_addc_u32 s49, s3, 0
	s_add_u32 s50, s2, s5
	s_addc_u32 s51, s3, 0
	s_add_u32 s52, s44, 0x12100000
	s_addc_u32 s53, s45, 0
	s_add_u32 s54, s44, 0x9100000
	s_addc_u32 s55, s45, 0
	s_mov_b32 s3, 0x1b100000
	s_mov_b32 s2, 0x9100000
	s_cmp_eq_u32 s9, 2
	s_cselect_b32 s2, s3, s2
	s_add_u32 s98, s44, s2
	s_addc_u32 s99, s45, 0
	s_branch .Lr0_row

; DI void row_phase(const PZ& p, int layer, int mode, int wave, int lane) {
;     ...
;     for (int m = gw; m < MTOK; m += NGW) {
;         const int b = m / TT, t = m - b * TT; const bool isc = t < NCTX; const int mr = isc ? 32 : b;
;         if (isc && layer == 3 && mode != 0) continue;
;         const size_t xoff = isc ? (size_t)(b * NCTX + t) * 1024 : (size_t)(b * NLAT + t - NCTX) * 1024;
;         const float* xs = (isc ? xc_src : xl_src) + xoff;
;         float* xd = (isc ? xc_dst : p.out()) + xoff;
.Lr0_row:
	s_mul_hi_i32 s21, s20, 0x38e38e39
	s_lshr_b32 s23, s21, 31
	s_ashr_i32 s21, s21, 9
	s_add_i32 s21, s21, s23
	s_mul_i32 s23, s21, 0xfffff700
	s_add_i32 s23, s23, s20
	s_cmpk_lt_i32 s23, 0x100
	s_cbranch_scc0 .Lr0_lat
	s_lshl_b32 s25, s21, 8
	s_add_i32 s25, s25, s23
	s_lshl_b32 s25, s25, 12
	s_add_u32 s2, s40, s25
	s_addc_u32 s3, s41, 0
	s_add_u32 s4, s46, s25
	s_addc_u32 s5, s47, 0
	s_mov_b32 s25, 32
	s_branch .Lr0_have

; DI void row_phase(const PZ& p, int layer, int mode, int wave, int lane) {
;     ...
;         f32x4 xv[4];
; #pragma unroll
;         for (int j = 0; j < 4; ++j) xv[j] = __builtin_nontemporal_load((const f32x4*)xs + lane + 64 * j);
;         if (mode != 0) {
;             f32x4 yv[4]; float ss = 0.f;
; #pragma unroll
;             for (int j = 0; j < 4; ++j) { yv[j] = bf4_to_f4(__builtin_nontemporal_load((const u32x2*)(Y + (size_t)m * 1024) + lane + 64 * j)); ss += yv[j].x * yv[j].x + yv[j].y * yv[j].y + yv[j].z * yv[j].z + yv[j].w * yv[j].w; }
;             const float rstd = rsqrtf(wave_sum(ss) * (1.f / 1024.f) + 1e-6f);
; #pragma unroll
;             for (int j = 0; j < 4; ++j) {
;                 const f32x4 gate = *((const f32x4*)(modl + (size_t)mr * 6144 + 2 * 1024) + lane + 64 * j);
;                 const f32x4 gp = *((const f32x4*)gpm + lane + 64 * j);
;                 xv[j] += gate * (yv[j] * rstd * gp);
;             }
;         }
;         if (mode == 2) {
;             f32x4 yv[4]; float ss = 0.f;
; #pragma unroll
;             for (int j = 0; j < 4; ++j) { yv[j] = bf4_to_f4(__builtin_nontemporal_load((const u32x2*)(F + (size_t)m * 1024) + lane + 64 * j)); ss += yv[j].x * yv[j].x + yv[j].y * yv[j].y + yv[j].z * yv[j].z + yv[j].w * yv[j].w; }
;             const float rstd = rsqrtf(wave_sum(ss) * (1.f / 1024.f) + 1e-6f);
; #pragma unroll
;             for (int j = 0; j < 4; ++j) {
;                 const f32x4 gate = *((const f32x4*)(modl + (size_t)mr * 6144 + 5 * 1024) + lane + 64 * j);
;                 const f32x4 gp = *((const f32x4*)gpl + lane + 64 * j);
;                 xv[j] += gate * (yv[j] * rstd * gp);
;                 *((f32x4*)xd + lane + 64 * j) = xv[j];
;             }
;         }
;         if (do_h) {
;             float ss = 0.f;
; #pragma unroll
;             for (int j = 0; j < 4; ++j) ss += xv[j].x * xv[j].x + xv[j].y * xv[j].y + xv[j].z * xv[j].z + xv[j].w * xv[j].w;
;             const float rstd = rsqrtf(wave_sum(ss) * (1.f / 1024.f) + 1e-6f);
; #pragma unroll
;             for (int j = 0; j < 4; ++j) {
;                 const f32x4 g = *((const f32x4*)gpre + lane + 64 * j);
;                 const f32x4 sh = *((const f32x4*)(modh + (size_t)mr * 6144 + shift_i * 1024) + lane + 64 * j);
;                 const f32x4 sc = *((const f32x4*)(modh + (size_t)mr * 6144 + scale_i * 1024) + lane + 64 * j);
.Lr0_have:
	s_mul_i32 s25, s25, 0x6000
	s_lshl_b32 s32, s20, 11
	global_load_dwordx4 v[52:55], v0, s[2:3] offset:0 nt
	global_load_dwordx4 v[56:59], v0, s[2:3] offset:1024 nt
	global_load_dwordx4 v[60:63], v0, s[2:3] offset:2048 nt
	global_load_dwordx4 v[64:67], v0, s[2:3] offset:3072 nt
	s_add_u32 s44, s98, s32
	s_addc_u32 s45, s99, 0
	s_add_u32 s34, s50, s25
	s_addc_u32 s35, s51, 0
	global_load_dwordx4 v[126:129], v0, s[34:35] offset:0
	global_load_dwordx4 v[130:133], v0, s[34:35] offset:1024
	global_load_dwordx4 v[134:137], v0, s[34:35] offset:2048
	global_load_dwordx4 v[138:141], v0, s[34:35] offset:3072
	s_add_u32 s6, s34, 0x1000
	s_addc_u32 s7, s35, 0
	global_load_dwordx4 v[170:173], v0, s[6:7] offset:0
	global_load_dwordx4 v[174:177], v0, s[6:7] offset:1024
	global_load_dwordx4 v[178:181], v0, s[6:7] offset:2048
	global_load_dwordx4 v[182:185], v0, s[6:7] offset:3072
	s_waitcnt vmcnt(8)
	s_cmp_eq_u32 s30, 0
	s_cbranch_scc1 .Lr0_next
	v_mul_f32_e32 v186, v52, v52
	v_mul_f32_e32 v187, v56, v56
	v_mul_f32_e32 v188, v60, v60
	v_mul_f32_e32 v189, v64, v64
	v_fmac_f32_e32 v186, v53, v53
	v_fmac_f32_e32 v187, v57, v57
	v_fmac_f32_e32 v188, v61, v61
	v_fmac_f32_e32 v189, v65, v65
	v_fmac_f32_e32 v186, v54, v54
	v_fmac_f32_e32 v187, v58, v58
	v_fmac_f32_e32 v188, v62, v62
	v_fmac_f32_e32 v189, v66, v66
	v_fmac_f32_e32 v186, v55, v55
	v_fmac_f32_e32 v187, v59, v59
	v_fmac_f32_e32 v188, v63, v63
	v_fmac_f32_e32 v189, v67, v67
	v_add_f32_e32 v186, v186, v187
	v_add_f32_e32 v188, v188, v189
	s_nop 0
	v_add_f32_e32 v186, v186, v188
	s_nop 1
	v_add_f32_dpp v186, v186, v186 quad_perm:[1,0,3,2] row_mask:0xf bank_mask:0xf bound_ctrl:1
	s_nop 1
	v_add_f32_dpp v186, v186, v186 quad_perm:[2,3,0,1] row_mask:0xf bank_mask:0xf bound_ctrl:1
	s_nop 1
	v_add_f32_dpp v186, v186, v186 row_half_mirror row_mask:0xf bank_mask:0xf bound_ctrl:1
	s_nop 1
	v_add_f32_dpp v186, v186, v186 row_mirror row_mask:0xf bank_mask:0xf bound_ctrl:1
	s_nop 1
	v_readlane_b32 s2, v186, 0
	v_readlane_b32 s3, v186, 16
	v_readlane_b32 s25, v186, 32
	v_readlane_b32 s32, v186, 48
	s_nop 1
	v_mov_b32_e32 v186, s2
	v_add_f32_e32 v186, s3, v186
	v_add_f32_e32 v186, s25, v186
	v_add_f32_e32 v186, s32, v186
	v_fmaak_f32 v186, v194, v186, 0x358637bd
	s_nop 0
	v_rsq_f32_e32 v186, v186
	s_waitcnt vmcnt(0)
	v_mul_f32_e32 v52, v52, v186
	v_mul_f32_e32 v56, v56, v186
	v_mul_f32_e32 v60, v60, v186
	v_mul_f32_e32 v64, v64, v186
	v_mul_f32_e32 v53, v53, v186
	v_mul_f32_e32 v57, v57, v186
	v_mul_f32_e32 v61, v61, v186
	v_mul_f32_e32 v65, v65, v186
	v_mul_f32_e32 v54, v54, v186
	v_mul_f32_e32 v58, v58, v186
	v_mul_f32_e32 v62, v62, v186
	v_mul_f32_e32 v66, v66, v186
	v_mul_f32_e32 v55, v55, v186
	v_mul_f32_e32 v59, v59, v186
	v_mul_f32_e32 v63, v63, v186
	v_mul_f32_e32 v67, v67, v186
	v_add_f32_e32 v170, 1.0, v170
	v_add_f32_e32 v174, 1.0, v174
	v_add_f32_e32 v178, 1.0, v178
	v_add_f32_e32 v182, 1.0, v182
	v_add_f32_e32 v171, 1.0, v171
	v_add_f32_e32 v175, 1.0, v175
	v_add_f32_e32 v179, 1.0, v179
	v_add_f32_e32 v183, 1.0, v183
	v_add_f32_e32 v172, 1.0, v172
	v_add_f32_e32 v176, 1.0, v176
	v_add_f32_e32 v180, 1.0, v180
	v_add_f32_e32 v184, 1.0, v184
	v_add_f32_e32 v173, 1.0, v173
	v_add_f32_e32 v177, 1.0, v177
	v_add_f32_e32 v181, 1.0, v181
	v_add_f32_e32 v185, 1.0, v185
	v_mul_f32_e32 v52, v52, v36
	v_mul_f32_e32 v56, v56, v40
	v_mul_f32_e32 v60, v60, v44
	v_mul_f32_e32 v64, v64, v48
	v_mul_f32_e32 v53, v53, v37
	v_mul_f32_e32 v57, v57, v41
	v_mul_f32_e32 v61, v61, v45
	v_mul_f32_e32 v65, v65, v49
	v_mul_f32_e32 v54, v54, v38
	v_mul_f32_e32 v58, v58, v42
	v_mul_f32_e32 v62, v62, v46
	v_mul_f32_e32 v66, v66, v50
	v_mul_f32_e32 v55, v55, v39
	v_mul_f32_e32 v59, v59, v43
	v_mul_f32_e32 v63, v63, v47
	v_mul_f32_e32 v67, v67, v51
	v_fma_f32 v52, v52, v170, v126
	v_fma_f32 v56, v56, v174, v130
	v_fma_f32 v60, v60, v178, v134
	v_fma_f32 v64, v64, v182, v138
	v_fma_f32 v53, v53, v171, v127
	v_fma_f32 v57, v57, v175, v131
	v_fma_f32 v61, v61, v179, v135
	v_fma_f32 v65, v65, v183, v139
	v_fma_f32 v54, v54, v172, v128
	v_fma_f32 v58, v58, v176, v132
	v_fma_f32 v62, v62, v180, v136
	v_fma_f32 v66, v66, v184, v140
	v_fma_f32 v55, v55, v173, v129
	v_fma_f32 v59, v59, v177, v133
	v_fma_f32 v63, v63, v181, v137
	v_fma_f32 v67, v67, v185, v141
	v_cvt_pk_bf16_f32 v186, v52, v53
	v_cvt_pk_bf16_f32 v187, v54, v55
	v_cvt_pk_bf16_f32 v188, v56, v57
	v_cvt_pk_bf16_f32 v189, v58, v59
	v_cvt_pk_bf16_f32 v190, v60, v61
	v_cvt_pk_bf16_f32 v191, v62, v63
	v_cvt_pk_bf16_f32 v192, v64, v65
	v_cvt_pk_bf16_f32 v193, v66, v67
	global_store_dwordx2 v1, v[186:187], s[44:45] offset:0
	global_store_dwordx2 v1, v[188:189], s[44:45] offset:512
	global_store_dwordx2 v1, v[190:191], s[44:45] offset:1024
	global_store_dwordx2 v1, v[192:193], s[44:45] offset:1536
	s_branch .Lr0_next
